# EM_RESID GEMM epilogue rewritten: residual loads run 8 deep ahead of add+store with counted vmcnt (was one load, full wait, one store at a time)
# speedup vs baseline: 1.0424x; 1.0092x over previous
; DI float sigmoidf_(float x) { return 1.0f / (1.0f + __expf(-x)); }
;     template <int W  > DI void flat_body(const f32x4 (&acc)[2][2][4][2], const int row0, const int col0) const {
; #pragma unroll
;         for (int bj = 0; bj < 2; ++bj)
; #pragma unroll
;             for (int n = 0; n < 2; ++n) {
;                 const int col = col0 + bj * HALF + n * 16;
;                 const f32x4 bv = bias ? *(const f32x4*)(bias + col) : (f32x4){0.f, 0.f, 0.f, 0.f};
; #pragma unroll
;                 for (int ai = 0; ai < 2; ++ai)
; #pragma unroll
;                     for (int m = 0; m < 4; ++m) {
;                         const size_t off = (size_t)(row0 + ai * HALF + m * 16) * ldc + col;
;                         f32x4 v = acc[ai][bj][m][n] + bv;
;                         if (W == 0) v = v + *(const f32x4*)((const float*)p1 + off);
;                         else if (W == 2) v = *(const f32x4*)((const float*)out + off) + 0.0f * v;
;                         else { v[0] = __expf(-0.60653066f * sigmoidf_(v[0])); v[1] = __expf(-0.60653066f * sigmoidf_(v[1])); v[2] = __expf(-0.60653066f * sigmoidf_(v[2])); v[3] = __expf(-0.60653066f * sigmoidf_(v[3])); }
;                         *(f32x4*)((float*)out + off) = v;
;                     }
;             }
;     }
.LBB0_619:
	s_and_b64 vcc, exec, s[10:11]
	s_cbranch_vccz .LBB0_634
	v_lshl_add_u32 v138, v192, 2, s31
	v_ashrrev_i32_e32 v139, 31, v138
	s_and_b64 vcc, exec, s[42:43]
	s_cbranch_vccnz .LresidA_nobias
	v_readlane_b32 s10, v233, 3
	v_readlane_b32 s11, v233, 4
	s_nop 1
	v_lshl_add_u64 v[136:137], v[138:139], 2, s[10:11]
	global_load_dwordx4 v[146:149], v[136:137], off
	global_load_dwordx4 v[150:153], v[136:137], off offset:64
	global_load_dwordx4 v[164:167], v[136:137], off offset:512
	global_load_dwordx4 v[168:171], v[136:137], off offset:576
	s_waitcnt vmcnt(0)
	v_pk_add_f32 v[126:127], v[126:127], v[146:147]
	v_pk_add_f32 v[128:129], v[128:129], v[148:149]
	v_pk_add_f32 v[122:123], v[122:123], v[146:147]
	v_pk_add_f32 v[124:125], v[124:125], v[148:149]
	v_pk_add_f32 v[118:119], v[118:119], v[146:147]
	v_pk_add_f32 v[120:121], v[120:121], v[148:149]
	v_pk_add_f32 v[114:115], v[114:115], v[146:147]
	v_pk_add_f32 v[116:117], v[116:117], v[148:149]
	v_pk_add_f32 v[110:111], v[110:111], v[146:147]
	v_pk_add_f32 v[112:113], v[112:113], v[148:149]
	v_pk_add_f32 v[106:107], v[106:107], v[146:147]
	v_pk_add_f32 v[108:109], v[108:109], v[148:149]
	v_pk_add_f32 v[102:103], v[102:103], v[146:147]
	v_pk_add_f32 v[104:105], v[104:105], v[148:149]
	v_pk_add_f32 v[98:99], v[98:99], v[146:147]
	v_pk_add_f32 v[100:101], v[100:101], v[148:149]
	v_pk_add_f32 v[92:93], v[92:93], v[150:151]
	v_pk_add_f32 v[94:95], v[94:95], v[152:153]
	v_pk_add_f32 v[88:89], v[88:89], v[150:151]
	v_pk_add_f32 v[90:91], v[90:91], v[152:153]
	v_pk_add_f32 v[84:85], v[84:85], v[150:151]
	v_pk_add_f32 v[86:87], v[86:87], v[152:153]
	v_pk_add_f32 v[80:81], v[80:81], v[150:151]
	v_pk_add_f32 v[82:83], v[82:83], v[152:153]
	v_pk_add_f32 v[76:77], v[76:77], v[150:151]
	v_pk_add_f32 v[78:79], v[78:79], v[152:153]
	v_pk_add_f32 v[72:73], v[72:73], v[150:151]
	v_pk_add_f32 v[74:75], v[74:75], v[152:153]
	v_pk_add_f32 v[68:69], v[68:69], v[150:151]
	v_pk_add_f32 v[70:71], v[70:71], v[152:153]
	v_pk_add_f32 v[64:65], v[64:65], v[150:151]
	v_pk_add_f32 v[66:67], v[66:67], v[152:153]
	v_pk_add_f32 v[60:61], v[60:61], v[164:165]
	v_pk_add_f32 v[62:63], v[62:63], v[166:167]
	v_pk_add_f32 v[56:57], v[56:57], v[164:165]
	v_pk_add_f32 v[58:59], v[58:59], v[166:167]
	v_pk_add_f32 v[52:53], v[52:53], v[164:165]
	v_pk_add_f32 v[54:55], v[54:55], v[166:167]
	v_pk_add_f32 v[48:49], v[48:49], v[164:165]
	v_pk_add_f32 v[50:51], v[50:51], v[166:167]
	v_pk_add_f32 v[44:45], v[44:45], v[164:165]
	v_pk_add_f32 v[46:47], v[46:47], v[166:167]
	v_pk_add_f32 v[40:41], v[40:41], v[164:165]
	v_pk_add_f32 v[42:43], v[42:43], v[166:167]
	v_pk_add_f32 v[36:37], v[36:37], v[164:165]
	v_pk_add_f32 v[38:39], v[38:39], v[166:167]
	v_pk_add_f32 v[32:33], v[32:33], v[164:165]
	v_pk_add_f32 v[34:35], v[34:35], v[166:167]
	v_pk_add_f32 v[28:29], v[28:29], v[168:169]
	v_pk_add_f32 v[30:31], v[30:31], v[170:171]
	v_pk_add_f32 v[24:25], v[24:25], v[168:169]
	v_pk_add_f32 v[26:27], v[26:27], v[170:171]
	v_pk_add_f32 v[20:21], v[20:21], v[168:169]
	v_pk_add_f32 v[22:23], v[22:23], v[170:171]
	v_pk_add_f32 v[16:17], v[16:17], v[168:169]
	v_pk_add_f32 v[18:19], v[18:19], v[170:171]
	v_pk_add_f32 v[12:13], v[12:13], v[168:169]
	v_pk_add_f32 v[14:15], v[14:15], v[170:171]
	v_pk_add_f32 v[8:9], v[8:9], v[168:169]
	v_pk_add_f32 v[10:11], v[10:11], v[170:171]
	v_pk_add_f32 v[4:5], v[4:5], v[168:169]
	v_pk_add_f32 v[6:7], v[6:7], v[170:171]
	v_pk_add_f32 v[0:1], v[0:1], v[168:169]
	v_pk_add_f32 v[2:3], v[2:3], v[170:171]
.LresidA_nobias:
	v_mad_i64_i32 v[196:197], s[10:11], v191, s75, v[138:139]
	v_add_u32_e32 v130, 0x10, v191
	v_mad_i64_i32 v[198:199], s[10:11], v130, s75, v[138:139]
	v_add_u32_e32 v130, 0x20, v191
	v_mad_i64_i32 v[200:201], s[10:11], v130, s75, v[138:139]
	v_add_u32_e32 v130, 0x30, v191
	v_mad_i64_i32 v[202:203], s[10:11], v130, s75, v[138:139]
	v_add_u32_e32 v130, 0x80, v191
	v_mad_i64_i32 v[204:205], s[10:11], v130, s75, v[138:139]
	v_add_u32_e32 v130, 0x90, v191
	v_mad_i64_i32 v[206:207], s[10:11], v130, s75, v[138:139]
	v_add_u32_e32 v130, 0xa0, v191
	v_mad_i64_i32 v[208:209], s[10:11], v130, s75, v[138:139]
	v_add_u32_e32 v130, 0xb0, v191
	v_mad_i64_i32 v[210:211], s[10:11], v130, s75, v[138:139]
	v_lshlrev_b64 v[196:197], 2, v[196:197]
	v_lshlrev_b64 v[198:199], 2, v[198:199]
	v_lshlrev_b64 v[200:201], 2, v[200:201]
	v_lshlrev_b64 v[202:203], 2, v[202:203]
	v_lshlrev_b64 v[204:205], 2, v[204:205]
	v_lshlrev_b64 v[206:207], 2, v[206:207]
	v_lshlrev_b64 v[208:209], 2, v[208:209]
	v_lshlrev_b64 v[210:211], 2, v[210:211]
	v_lshl_add_u64 v[144:145], s[2:3], 0, v[196:197]
	global_load_dwordx4 v[146:149], v[144:145], off
	v_lshl_add_u64 v[144:145], s[2:3], 0, v[198:199]
	global_load_dwordx4 v[150:153], v[144:145], off
	v_lshl_add_u64 v[144:145], s[2:3], 0, v[200:201]
	global_load_dwordx4 v[164:167], v[144:145], off
	v_lshl_add_u64 v[144:145], s[2:3], 0, v[202:203]
	global_load_dwordx4 v[168:171], v[144:145], off
	v_lshl_add_u64 v[144:145], s[2:3], 0, v[204:205]
	global_load_dwordx4 v[172:175], v[144:145], off
	v_lshl_add_u64 v[144:145], s[2:3], 0, v[206:207]
	global_load_dwordx4 v[176:179], v[144:145], off
	v_lshl_add_u64 v[144:145], s[2:3], 0, v[208:209]
	global_load_dwordx4 v[212:215], v[144:145], off
	v_lshl_add_u64 v[144:145], s[2:3], 0, v[210:211]
	global_load_dwordx4 v[140:143], v[144:145], off
	s_waitcnt vmcnt(7)
	v_pk_add_f32 v[146:147], v[146:147], v[126:127]
	v_pk_add_f32 v[148:149], v[148:149], v[128:129]
	v_lshl_add_u64 v[216:217], s[76:77], 0, v[196:197]
	global_store_dwordx4 v[216:217], v[146:149], off
	v_lshl_add_u64 v[144:145], s[2:3], 0, v[196:197]
	global_load_dwordx4 v[146:149], v[144:145], off offset:64
	s_waitcnt vmcnt(8)
; DI float sigmoidf_(float x) { return 1.0f / (1.0f + __expf(-x)); }
;     template <int W  > DI void flat_body(const f32x4 (&acc)[2][2][4][2], const int row0, const int col0) const {
;     ...
;                 for (int ai = 0; ai < 2; ++ai)
; #pragma unroll
;                     for (int m = 0; m < 4; ++m) {
;                         const size_t off = (size_t)(row0 + ai * HALF + m * 16) * ldc + col;
;                         f32x4 v = acc[ai][bj][m][n] + bv;
;                         if (W == 0) v = v + *(const f32x4*)((const float*)p1 + off);
;                         else if (W == 2) v = *(const f32x4*)((const float*)out + off) + 0.0f * v;
;                         else { v[0] = __expf(-0.60653066f * sigmoidf_(v[0])); v[1] = __expf(-0.60653066f * sigmoidf_(v[1])); v[2] = __expf(-0.60653066f * sigmoidf_(v[2])); v[3] = __expf(-0.60653066f * sigmoidf_(v[3])); }
;                         *(f32x4*)((float*)out + off) = v;
	v_pk_add_f32 v[150:151], v[150:151], v[122:123]
	v_pk_add_f32 v[152:153], v[152:153], v[124:125]
	v_lshl_add_u64 v[216:217], s[76:77], 0, v[198:199]
	global_store_dwordx4 v[216:217], v[150:153], off
	v_lshl_add_u64 v[144:145], s[2:3], 0, v[198:199]
	global_load_dwordx4 v[150:153], v[144:145], off offset:64
	s_waitcnt vmcnt(9)
	v_pk_add_f32 v[164:165], v[164:165], v[118:119]
	v_pk_add_f32 v[166:167], v[166:167], v[120:121]
	v_lshl_add_u64 v[216:217], s[76:77], 0, v[200:201]
	global_store_dwordx4 v[216:217], v[164:167], off
	v_lshl_add_u64 v[144:145], s[2:3], 0, v[200:201]
	global_load_dwordx4 v[164:167], v[144:145], off offset:64
	s_waitcnt vmcnt(10)
	v_pk_add_f32 v[168:169], v[168:169], v[114:115]
	v_pk_add_f32 v[170:171], v[170:171], v[116:117]
	v_lshl_add_u64 v[216:217], s[76:77], 0, v[202:203]
	global_store_dwordx4 v[216:217], v[168:171], off
	v_lshl_add_u64 v[144:145], s[2:3], 0, v[202:203]
	global_load_dwordx4 v[168:171], v[144:145], off offset:64
	s_waitcnt vmcnt(11)
	v_pk_add_f32 v[172:173], v[172:173], v[110:111]
	v_pk_add_f32 v[174:175], v[174:175], v[112:113]
	v_lshl_add_u64 v[216:217], s[76:77], 0, v[204:205]
	global_store_dwordx4 v[216:217], v[172:175], off
	v_lshl_add_u64 v[144:145], s[2:3], 0, v[204:205]
	global_load_dwordx4 v[172:175], v[144:145], off offset:64
	s_waitcnt vmcnt(12)
	v_pk_add_f32 v[176:177], v[176:177], v[106:107]
	v_pk_add_f32 v[178:179], v[178:179], v[108:109]
	v_lshl_add_u64 v[216:217], s[76:77], 0, v[206:207]
	global_store_dwordx4 v[216:217], v[176:179], off
	v_lshl_add_u64 v[144:145], s[2:3], 0, v[206:207]
	global_load_dwordx4 v[176:179], v[144:145], off offset:64
	s_waitcnt vmcnt(13)
	v_pk_add_f32 v[212:213], v[212:213], v[102:103]
	v_pk_add_f32 v[214:215], v[214:215], v[104:105]
	v_lshl_add_u64 v[216:217], s[76:77], 0, v[208:209]
	global_store_dwordx4 v[216:217], v[212:215], off
	v_lshl_add_u64 v[144:145], s[2:3], 0, v[208:209]
	global_load_dwordx4 v[212:215], v[144:145], off offset:64
	s_waitcnt vmcnt(14)
	v_pk_add_f32 v[140:141], v[140:141], v[98:99]
	v_pk_add_f32 v[142:143], v[142:143], v[100:101]
	v_lshl_add_u64 v[216:217], s[76:77], 0, v[210:211]
	global_store_dwordx4 v[216:217], v[140:143], off
	v_lshl_add_u64 v[144:145], s[2:3], 0, v[210:211]
	global_load_dwordx4 v[140:143], v[144:145], off offset:64
	s_waitcnt vmcnt(14)
	v_pk_add_f32 v[146:147], v[146:147], v[92:93]
	v_pk_add_f32 v[148:149], v[148:149], v[94:95]
	v_lshl_add_u64 v[216:217], s[76:77], 0, v[196:197]
	global_store_dwordx4 v[216:217], v[146:149], off offset:64
	v_lshl_add_u64 v[144:145], s[2:3], 0, v[196:197]
	global_load_dwordx4 v[146:149], v[144:145], off offset:512
	s_waitcnt vmcnt(14)
	v_pk_add_f32 v[150:151], v[150:151], v[88:89]
	v_pk_add_f32 v[152:153], v[152:153], v[90:91]
	v_lshl_add_u64 v[216:217], s[76:77], 0, v[198:199]
	global_store_dwordx4 v[216:217], v[150:153], off offset:64
	v_lshl_add_u64 v[144:145], s[2:3], 0, v[198:199]
	global_load_dwordx4 v[150:153], v[144:145], off offset:512
	s_waitcnt vmcnt(14)
	v_pk_add_f32 v[164:165], v[164:165], v[84:85]
	v_pk_add_f32 v[166:167], v[166:167], v[86:87]
	v_lshl_add_u64 v[216:217], s[76:77], 0, v[200:201]
	global_store_dwordx4 v[216:217], v[164:167], off offset:64
	v_lshl_add_u64 v[144:145], s[2:3], 0, v[200:201]
	global_load_dwordx4 v[164:167], v[144:145], off offset:512
	s_waitcnt vmcnt(14)
	v_pk_add_f32 v[168:169], v[168:169], v[80:81]
	v_pk_add_f32 v[170:171], v[170:171], v[82:83]
	v_lshl_add_u64 v[216:217], s[76:77], 0, v[202:203]
	global_store_dwordx4 v[216:217], v[168:171], off offset:64
	v_lshl_add_u64 v[144:145], s[2:3], 0, v[202:203]
	global_load_dwordx4 v[168:171], v[144:145], off offset:512
	s_waitcnt vmcnt(14)
	v_pk_add_f32 v[172:173], v[172:173], v[76:77]
	v_pk_add_f32 v[174:175], v[174:175], v[78:79]
	v_lshl_add_u64 v[216:217], s[76:77], 0, v[204:205]
	global_store_dwordx4 v[216:217], v[172:175], off offset:64
	v_lshl_add_u64 v[144:145], s[2:3], 0, v[204:205]
	global_load_dwordx4 v[172:175], v[144:145], off offset:512
	s_waitcnt vmcnt(14)
	v_pk_add_f32 v[176:177], v[176:177], v[72:73]
	v_pk_add_f32 v[178:179], v[178:179], v[74:75]
	v_lshl_add_u64 v[216:217], s[76:77], 0, v[206:207]
	global_store_dwordx4 v[216:217], v[176:179], off offset:64
	v_lshl_add_u64 v[144:145], s[2:3], 0, v[206:207]
	global_load_dwordx4 v[176:179], v[144:145], off offset:512
	s_waitcnt vmcnt(14)
	v_pk_add_f32 v[212:213], v[212:213], v[68:69]
	v_pk_add_f32 v[214:215], v[214:215], v[70:71]
	v_lshl_add_u64 v[216:217], s[76:77], 0, v[208:209]
	global_store_dwordx4 v[216:217], v[212:215], off offset:64
	v_lshl_add_u64 v[144:145], s[2:3], 0, v[208:209]
	global_load_dwordx4 v[212:215], v[144:145], off offset:512
	s_waitcnt vmcnt(14)
; DI float sigmoidf_(float x) { return 1.0f / (1.0f + __expf(-x)); }
;     template <int W  > DI void flat_body(const f32x4 (&acc)[2][2][4][2], const int row0, const int col0) const {
;     ...
;                 for (int ai = 0; ai < 2; ++ai)
; #pragma unroll
;                     for (int m = 0; m < 4; ++m) {
;                         const size_t off = (size_t)(row0 + ai * HALF + m * 16) * ldc + col;
;                         f32x4 v = acc[ai][bj][m][n] + bv;
;                         if (W == 0) v = v + *(const f32x4*)((const float*)p1 + off);
;                         else if (W == 2) v = *(const f32x4*)((const float*)out + off) + 0.0f * v;
;                         else { v[0] = __expf(-0.60653066f * sigmoidf_(v[0])); v[1] = __expf(-0.60653066f * sigmoidf_(v[1])); v[2] = __expf(-0.60653066f * sigmoidf_(v[2])); v[3] = __expf(-0.60653066f * sigmoidf_(v[3])); }
;                         *(f32x4*)((float*)out + off) = v;
	v_pk_add_f32 v[140:141], v[140:141], v[64:65]
	v_pk_add_f32 v[142:143], v[142:143], v[66:67]
	v_lshl_add_u64 v[216:217], s[76:77], 0, v[210:211]
	global_store_dwordx4 v[216:217], v[140:143], off offset:64
	v_lshl_add_u64 v[144:145], s[2:3], 0, v[210:211]
	global_load_dwordx4 v[140:143], v[144:145], off offset:512
	s_waitcnt vmcnt(14)
	v_pk_add_f32 v[146:147], v[146:147], v[60:61]
	v_pk_add_f32 v[148:149], v[148:149], v[62:63]
	v_lshl_add_u64 v[216:217], s[76:77], 0, v[196:197]
	global_store_dwordx4 v[216:217], v[146:149], off offset:512
	v_lshl_add_u64 v[144:145], s[2:3], 0, v[196:197]
	global_load_dwordx4 v[146:149], v[144:145], off offset:576
	s_waitcnt vmcnt(14)
	v_pk_add_f32 v[150:151], v[150:151], v[56:57]
	v_pk_add_f32 v[152:153], v[152:153], v[58:59]
	v_lshl_add_u64 v[216:217], s[76:77], 0, v[198:199]
	global_store_dwordx4 v[216:217], v[150:153], off offset:512
	v_lshl_add_u64 v[144:145], s[2:3], 0, v[198:199]
	global_load_dwordx4 v[150:153], v[144:145], off offset:576
	s_waitcnt vmcnt(14)
	v_pk_add_f32 v[164:165], v[164:165], v[52:53]
	v_pk_add_f32 v[166:167], v[166:167], v[54:55]
	v_lshl_add_u64 v[216:217], s[76:77], 0, v[200:201]
	global_store_dwordx4 v[216:217], v[164:167], off offset:512
	v_lshl_add_u64 v[144:145], s[2:3], 0, v[200:201]
	global_load_dwordx4 v[164:167], v[144:145], off offset:576
	s_waitcnt vmcnt(14)
	v_pk_add_f32 v[168:169], v[168:169], v[48:49]
	v_pk_add_f32 v[170:171], v[170:171], v[50:51]
	v_lshl_add_u64 v[216:217], s[76:77], 0, v[202:203]
	global_store_dwordx4 v[216:217], v[168:171], off offset:512
	v_lshl_add_u64 v[144:145], s[2:3], 0, v[202:203]
	global_load_dwordx4 v[168:171], v[144:145], off offset:576
	s_waitcnt vmcnt(14)
	v_pk_add_f32 v[172:173], v[172:173], v[44:45]
	v_pk_add_f32 v[174:175], v[174:175], v[46:47]
	v_lshl_add_u64 v[216:217], s[76:77], 0, v[204:205]
	global_store_dwordx4 v[216:217], v[172:175], off offset:512
	v_lshl_add_u64 v[144:145], s[2:3], 0, v[204:205]
	global_load_dwordx4 v[172:175], v[144:145], off offset:576
	s_waitcnt vmcnt(14)
	v_pk_add_f32 v[176:177], v[176:177], v[40:41]
	v_pk_add_f32 v[178:179], v[178:179], v[42:43]
	v_lshl_add_u64 v[216:217], s[76:77], 0, v[206:207]
	global_store_dwordx4 v[216:217], v[176:179], off offset:512
	v_lshl_add_u64 v[144:145], s[2:3], 0, v[206:207]
	global_load_dwordx4 v[176:179], v[144:145], off offset:576
	s_waitcnt vmcnt(14)
	v_pk_add_f32 v[212:213], v[212:213], v[36:37]
	v_pk_add_f32 v[214:215], v[214:215], v[38:39]
	v_lshl_add_u64 v[216:217], s[76:77], 0, v[208:209]
	global_store_dwordx4 v[216:217], v[212:215], off offset:512
	v_lshl_add_u64 v[144:145], s[2:3], 0, v[208:209]
	global_load_dwordx4 v[212:215], v[144:145], off offset:576
	s_waitcnt vmcnt(14)
	v_pk_add_f32 v[140:141], v[140:141], v[32:33]
	v_pk_add_f32 v[142:143], v[142:143], v[34:35]
	v_lshl_add_u64 v[216:217], s[76:77], 0, v[210:211]
	global_store_dwordx4 v[216:217], v[140:143], off offset:512
	v_lshl_add_u64 v[144:145], s[2:3], 0, v[210:211]
	global_load_dwordx4 v[140:143], v[144:145], off offset:576
	s_waitcnt vmcnt(14)
	v_pk_add_f32 v[146:147], v[146:147], v[28:29]
	v_pk_add_f32 v[148:149], v[148:149], v[30:31]
	v_lshl_add_u64 v[216:217], s[76:77], 0, v[196:197]
	global_store_dwordx4 v[216:217], v[146:149], off offset:576
	s_waitcnt vmcnt(13)
	v_pk_add_f32 v[150:151], v[150:151], v[24:25]
	v_pk_add_f32 v[152:153], v[152:153], v[26:27]
	v_lshl_add_u64 v[216:217], s[76:77], 0, v[198:199]
	global_store_dwordx4 v[216:217], v[150:153], off offset:576
	s_waitcnt vmcnt(12)
	v_pk_add_f32 v[164:165], v[164:165], v[20:21]
	v_pk_add_f32 v[166:167], v[166:167], v[22:23]
	v_lshl_add_u64 v[216:217], s[76:77], 0, v[200:201]
	global_store_dwordx4 v[216:217], v[164:167], off offset:576
	s_waitcnt vmcnt(11)
	v_pk_add_f32 v[168:169], v[168:169], v[16:17]
	v_pk_add_f32 v[170:171], v[170:171], v[18:19]
	v_lshl_add_u64 v[216:217], s[76:77], 0, v[202:203]
	global_store_dwordx4 v[216:217], v[168:171], off offset:576
	s_waitcnt vmcnt(10)
	v_pk_add_f32 v[172:173], v[172:173], v[12:13]
	v_pk_add_f32 v[174:175], v[174:175], v[14:15]
	v_lshl_add_u64 v[216:217], s[76:77], 0, v[204:205]
	global_store_dwordx4 v[216:217], v[172:175], off offset:576
	s_waitcnt vmcnt(9)
	v_pk_add_f32 v[176:177], v[176:177], v[8:9]
	v_pk_add_f32 v[178:179], v[178:179], v[10:11]
	v_lshl_add_u64 v[216:217], s[76:77], 0, v[206:207]
	global_store_dwordx4 v[216:217], v[176:179], off offset:576
	s_waitcnt vmcnt(8)
	v_pk_add_f32 v[212:213], v[212:213], v[4:5]
	v_pk_add_f32 v[214:215], v[214:215], v[6:7]
	v_lshl_add_u64 v[216:217], s[76:77], 0, v[208:209]
	global_store_dwordx4 v[216:217], v[212:215], off offset:576
	s_waitcnt vmcnt(7)
	v_pk_add_f32 v[140:141], v[140:141], v[0:1]
	v_pk_add_f32 v[142:143], v[142:143], v[2:3]
	v_lshl_add_u64 v[216:217], s[76:77], 0, v[210:211]
	global_store_dwordx4 v[216:217], v[140:143], off offset:576
	s_and_b64 vcc, exec, s[40:41]
	s_mov_b64 s[10:11], -1
	s_cbranch_vccnz .LBB0_590
	s_branch .LBB0_635

; DI float sigmoidf_(float x) { return 1.0f / (1.0f + __expf(-x)); }
;     template <int W  > DI void flat_body(const f32x4 (&acc)[2][2][4][2], const int row0, const int col0) const {
; #pragma unroll
;         for (int bj = 0; bj < 2; ++bj)
; #pragma unroll
;             for (int n = 0; n < 2; ++n) {
;                 const int col = col0 + bj * HALF + n * 16;
;                 const f32x4 bv = bias ? *(const f32x4*)(bias + col) : (f32x4){0.f, 0.f, 0.f, 0.f};
; #pragma unroll
;                 for (int ai = 0; ai < 2; ++ai)
; #pragma unroll
;                     for (int m = 0; m < 4; ++m) {
;                         const size_t off = (size_t)(row0 + ai * HALF + m * 16) * ldc + col;
;                         f32x4 v = acc[ai][bj][m][n] + bv;
;                         if (W == 0) v = v + *(const f32x4*)((const float*)p1 + off);
;                         else if (W == 2) v = *(const f32x4*)((const float*)out + off) + 0.0f * v;
;                         else { v[0] = __expf(-0.60653066f * sigmoidf_(v[0])); v[1] = __expf(-0.60653066f * sigmoidf_(v[1])); v[2] = __expf(-0.60653066f * sigmoidf_(v[2])); v[3] = __expf(-0.60653066f * sigmoidf_(v[3])); }
;                         *(f32x4*)((float*)out + off) = v;
;                     }
;             }
;     }
.LBB0_843:
	s_and_b64 vcc, exec, s[0:1]
	s_cbranch_vccz .LBB0_858
	v_lshl_add_u32 v138, v192, 2, s31
	v_ashrrev_i32_e32 v139, 31, v138
	s_cmp_lg_u64 s[10:11], 0
	s_cselect_b64 s[12:13], -1, 0
	s_cmp_eq_u64 s[10:11], 0
	s_cbranch_scc1 .LresidB_nobias
	v_lshl_add_u64 v[136:137], v[138:139], 2, s[10:11]
	global_load_dwordx4 v[146:149], v[136:137], off
	global_load_dwordx4 v[150:153], v[136:137], off offset:64
	global_load_dwordx4 v[164:167], v[136:137], off offset:512
	global_load_dwordx4 v[168:171], v[136:137], off offset:576
	s_waitcnt vmcnt(0)
	v_pk_add_f32 v[126:127], v[126:127], v[146:147]
	v_pk_add_f32 v[128:129], v[128:129], v[148:149]
	v_pk_add_f32 v[122:123], v[122:123], v[146:147]
	v_pk_add_f32 v[124:125], v[124:125], v[148:149]
	v_pk_add_f32 v[118:119], v[118:119], v[146:147]
	v_pk_add_f32 v[120:121], v[120:121], v[148:149]
	v_pk_add_f32 v[114:115], v[114:115], v[146:147]
	v_pk_add_f32 v[116:117], v[116:117], v[148:149]
	v_pk_add_f32 v[110:111], v[110:111], v[146:147]
	v_pk_add_f32 v[112:113], v[112:113], v[148:149]
	v_pk_add_f32 v[106:107], v[106:107], v[146:147]
	v_pk_add_f32 v[108:109], v[108:109], v[148:149]
	v_pk_add_f32 v[102:103], v[102:103], v[146:147]
	v_pk_add_f32 v[104:105], v[104:105], v[148:149]
	v_pk_add_f32 v[98:99], v[98:99], v[146:147]
	v_pk_add_f32 v[100:101], v[100:101], v[148:149]
	v_pk_add_f32 v[92:93], v[92:93], v[150:151]
	v_pk_add_f32 v[94:95], v[94:95], v[152:153]
	v_pk_add_f32 v[88:89], v[88:89], v[150:151]
	v_pk_add_f32 v[90:91], v[90:91], v[152:153]
	v_pk_add_f32 v[84:85], v[84:85], v[150:151]
	v_pk_add_f32 v[86:87], v[86:87], v[152:153]
	v_pk_add_f32 v[80:81], v[80:81], v[150:151]
	v_pk_add_f32 v[82:83], v[82:83], v[152:153]
	v_pk_add_f32 v[76:77], v[76:77], v[150:151]
	v_pk_add_f32 v[78:79], v[78:79], v[152:153]
	v_pk_add_f32 v[72:73], v[72:73], v[150:151]
	v_pk_add_f32 v[74:75], v[74:75], v[152:153]
	v_pk_add_f32 v[68:69], v[68:69], v[150:151]
	v_pk_add_f32 v[70:71], v[70:71], v[152:153]
	v_pk_add_f32 v[64:65], v[64:65], v[150:151]
	v_pk_add_f32 v[66:67], v[66:67], v[152:153]
	v_pk_add_f32 v[60:61], v[60:61], v[164:165]
	v_pk_add_f32 v[62:63], v[62:63], v[166:167]
	v_pk_add_f32 v[56:57], v[56:57], v[164:165]
	v_pk_add_f32 v[58:59], v[58:59], v[166:167]
	v_pk_add_f32 v[52:53], v[52:53], v[164:165]
	v_pk_add_f32 v[54:55], v[54:55], v[166:167]
	v_pk_add_f32 v[48:49], v[48:49], v[164:165]
	v_pk_add_f32 v[50:51], v[50:51], v[166:167]
	v_pk_add_f32 v[44:45], v[44:45], v[164:165]
	v_pk_add_f32 v[46:47], v[46:47], v[166:167]
	v_pk_add_f32 v[40:41], v[40:41], v[164:165]
	v_pk_add_f32 v[42:43], v[42:43], v[166:167]
	v_pk_add_f32 v[36:37], v[36:37], v[164:165]
	v_pk_add_f32 v[38:39], v[38:39], v[166:167]
	v_pk_add_f32 v[32:33], v[32:33], v[164:165]
	v_pk_add_f32 v[34:35], v[34:35], v[166:167]
	v_pk_add_f32 v[28:29], v[28:29], v[168:169]
	v_pk_add_f32 v[30:31], v[30:31], v[170:171]
	v_pk_add_f32 v[24:25], v[24:25], v[168:169]
	v_pk_add_f32 v[26:27], v[26:27], v[170:171]
	v_pk_add_f32 v[20:21], v[20:21], v[168:169]
	v_pk_add_f32 v[22:23], v[22:23], v[170:171]
	v_pk_add_f32 v[16:17], v[16:17], v[168:169]
	v_pk_add_f32 v[18:19], v[18:19], v[170:171]
	v_pk_add_f32 v[12:13], v[12:13], v[168:169]
	v_pk_add_f32 v[14:15], v[14:15], v[170:171]
	v_pk_add_f32 v[8:9], v[8:9], v[168:169]
	v_pk_add_f32 v[10:11], v[10:11], v[170:171]
	v_pk_add_f32 v[4:5], v[4:5], v[168:169]
	v_pk_add_f32 v[6:7], v[6:7], v[170:171]
	v_pk_add_f32 v[0:1], v[0:1], v[168:169]
	v_pk_add_f32 v[2:3], v[2:3], v[170:171]
.LresidB_nobias:
	v_mad_i64_i32 v[196:197], s[0:1], v191, s30, v[138:139]
	v_add_u32_e32 v130, 0x10, v191
	v_mad_i64_i32 v[198:199], s[0:1], v130, s30, v[138:139]
	v_add_u32_e32 v130, 0x20, v191
	v_mad_i64_i32 v[200:201], s[0:1], v130, s30, v[138:139]
	v_add_u32_e32 v130, 0x30, v191
	v_mad_i64_i32 v[202:203], s[0:1], v130, s30, v[138:139]
	v_add_u32_e32 v130, 0x80, v191
	v_mad_i64_i32 v[204:205], s[0:1], v130, s30, v[138:139]
	v_add_u32_e32 v130, 0x90, v191
	v_mad_i64_i32 v[206:207], s[0:1], v130, s30, v[138:139]
	v_add_u32_e32 v130, 0xa0, v191
	v_mad_i64_i32 v[208:209], s[0:1], v130, s30, v[138:139]
	v_add_u32_e32 v130, 0xb0, v191
	v_mad_i64_i32 v[210:211], s[0:1], v130, s30, v[138:139]
	v_lshlrev_b64 v[196:197], 2, v[196:197]
	v_lshlrev_b64 v[198:199], 2, v[198:199]
	v_lshlrev_b64 v[200:201], 2, v[200:201]
	v_lshlrev_b64 v[202:203], 2, v[202:203]
	v_lshlrev_b64 v[204:205], 2, v[204:205]
	v_lshlrev_b64 v[206:207], 2, v[206:207]
	v_lshlrev_b64 v[208:209], 2, v[208:209]
	v_lshlrev_b64 v[210:211], 2, v[210:211]
	v_lshl_add_u64 v[144:145], s[8:9], 0, v[196:197]
	global_load_dwordx4 v[146:149], v[144:145], off
	v_lshl_add_u64 v[144:145], s[8:9], 0, v[198:199]
	global_load_dwordx4 v[150:153], v[144:145], off
	v_lshl_add_u64 v[144:145], s[8:9], 0, v[200:201]
	global_load_dwordx4 v[164:167], v[144:145], off
	v_lshl_add_u64 v[144:145], s[8:9], 0, v[202:203]
	global_load_dwordx4 v[168:171], v[144:145], off
	v_lshl_add_u64 v[144:145], s[8:9], 0, v[204:205]
	global_load_dwordx4 v[172:175], v[144:145], off
	v_lshl_add_u64 v[144:145], s[8:9], 0, v[206:207]
	global_load_dwordx4 v[176:179], v[144:145], off
	v_lshl_add_u64 v[144:145], s[8:9], 0, v[208:209]
	global_load_dwordx4 v[212:215], v[144:145], off
	v_lshl_add_u64 v[144:145], s[8:9], 0, v[210:211]
	global_load_dwordx4 v[140:143], v[144:145], off
	s_waitcnt vmcnt(7)
	v_pk_add_f32 v[146:147], v[146:147], v[126:127]
	v_pk_add_f32 v[148:149], v[148:149], v[128:129]
	v_lshl_add_u64 v[216:217], s[6:7], 0, v[196:197]
	global_store_dwordx4 v[216:217], v[146:149], off
	v_lshl_add_u64 v[144:145], s[8:9], 0, v[196:197]
	global_load_dwordx4 v[146:149], v[144:145], off offset:64
	s_waitcnt vmcnt(8)
; DI float sigmoidf_(float x) { return 1.0f / (1.0f + __expf(-x)); }
;     template <int W  > DI void flat_body(const f32x4 (&acc)[2][2][4][2], const int row0, const int col0) const {
;     ...
;                 for (int ai = 0; ai < 2; ++ai)
; #pragma unroll
;                     for (int m = 0; m < 4; ++m) {
;                         const size_t off = (size_t)(row0 + ai * HALF + m * 16) * ldc + col;
;                         f32x4 v = acc[ai][bj][m][n] + bv;
;                         if (W == 0) v = v + *(const f32x4*)((const float*)p1 + off);
;                         else if (W == 2) v = *(const f32x4*)((const float*)out + off) + 0.0f * v;
;                         else { v[0] = __expf(-0.60653066f * sigmoidf_(v[0])); v[1] = __expf(-0.60653066f * sigmoidf_(v[1])); v[2] = __expf(-0.60653066f * sigmoidf_(v[2])); v[3] = __expf(-0.60653066f * sigmoidf_(v[3])); }
;                         *(f32x4*)((float*)out + off) = v;
	v_pk_add_f32 v[150:151], v[150:151], v[122:123]
	v_pk_add_f32 v[152:153], v[152:153], v[124:125]
	v_lshl_add_u64 v[216:217], s[6:7], 0, v[198:199]
	global_store_dwordx4 v[216:217], v[150:153], off
	v_lshl_add_u64 v[144:145], s[8:9], 0, v[198:199]
	global_load_dwordx4 v[150:153], v[144:145], off offset:64
	s_waitcnt vmcnt(9)
	v_pk_add_f32 v[164:165], v[164:165], v[118:119]
	v_pk_add_f32 v[166:167], v[166:167], v[120:121]
	v_lshl_add_u64 v[216:217], s[6:7], 0, v[200:201]
	global_store_dwordx4 v[216:217], v[164:167], off
	v_lshl_add_u64 v[144:145], s[8:9], 0, v[200:201]
	global_load_dwordx4 v[164:167], v[144:145], off offset:64
	s_waitcnt vmcnt(10)
	v_pk_add_f32 v[168:169], v[168:169], v[114:115]
	v_pk_add_f32 v[170:171], v[170:171], v[116:117]
	v_lshl_add_u64 v[216:217], s[6:7], 0, v[202:203]
	global_store_dwordx4 v[216:217], v[168:171], off
	v_lshl_add_u64 v[144:145], s[8:9], 0, v[202:203]
	global_load_dwordx4 v[168:171], v[144:145], off offset:64
	s_waitcnt vmcnt(11)
	v_pk_add_f32 v[172:173], v[172:173], v[110:111]
	v_pk_add_f32 v[174:175], v[174:175], v[112:113]
	v_lshl_add_u64 v[216:217], s[6:7], 0, v[204:205]
	global_store_dwordx4 v[216:217], v[172:175], off
	v_lshl_add_u64 v[144:145], s[8:9], 0, v[204:205]
	global_load_dwordx4 v[172:175], v[144:145], off offset:64
	s_waitcnt vmcnt(12)
	v_pk_add_f32 v[176:177], v[176:177], v[106:107]
	v_pk_add_f32 v[178:179], v[178:179], v[108:109]
	v_lshl_add_u64 v[216:217], s[6:7], 0, v[206:207]
	global_store_dwordx4 v[216:217], v[176:179], off
	v_lshl_add_u64 v[144:145], s[8:9], 0, v[206:207]
	global_load_dwordx4 v[176:179], v[144:145], off offset:64
	s_waitcnt vmcnt(13)
	v_pk_add_f32 v[212:213], v[212:213], v[102:103]
	v_pk_add_f32 v[214:215], v[214:215], v[104:105]
	v_lshl_add_u64 v[216:217], s[6:7], 0, v[208:209]
	global_store_dwordx4 v[216:217], v[212:215], off
	v_lshl_add_u64 v[144:145], s[8:9], 0, v[208:209]
	global_load_dwordx4 v[212:215], v[144:145], off offset:64
	s_waitcnt vmcnt(14)
	v_pk_add_f32 v[140:141], v[140:141], v[98:99]
	v_pk_add_f32 v[142:143], v[142:143], v[100:101]
	v_lshl_add_u64 v[216:217], s[6:7], 0, v[210:211]
	global_store_dwordx4 v[216:217], v[140:143], off
	v_lshl_add_u64 v[144:145], s[8:9], 0, v[210:211]
	global_load_dwordx4 v[140:143], v[144:145], off offset:64
	s_waitcnt vmcnt(14)
	v_pk_add_f32 v[146:147], v[146:147], v[92:93]
	v_pk_add_f32 v[148:149], v[148:149], v[94:95]
	v_lshl_add_u64 v[216:217], s[6:7], 0, v[196:197]
	global_store_dwordx4 v[216:217], v[146:149], off offset:64
	v_lshl_add_u64 v[144:145], s[8:9], 0, v[196:197]
	global_load_dwordx4 v[146:149], v[144:145], off offset:512
	s_waitcnt vmcnt(14)
	v_pk_add_f32 v[150:151], v[150:151], v[88:89]
	v_pk_add_f32 v[152:153], v[152:153], v[90:91]
	v_lshl_add_u64 v[216:217], s[6:7], 0, v[198:199]
	global_store_dwordx4 v[216:217], v[150:153], off offset:64
	v_lshl_add_u64 v[144:145], s[8:9], 0, v[198:199]
	global_load_dwordx4 v[150:153], v[144:145], off offset:512
	s_waitcnt vmcnt(14)
	v_pk_add_f32 v[164:165], v[164:165], v[84:85]
	v_pk_add_f32 v[166:167], v[166:167], v[86:87]
	v_lshl_add_u64 v[216:217], s[6:7], 0, v[200:201]
	global_store_dwordx4 v[216:217], v[164:167], off offset:64
	v_lshl_add_u64 v[144:145], s[8:9], 0, v[200:201]
	global_load_dwordx4 v[164:167], v[144:145], off offset:512
	s_waitcnt vmcnt(14)
	v_pk_add_f32 v[168:169], v[168:169], v[80:81]
	v_pk_add_f32 v[170:171], v[170:171], v[82:83]
	v_lshl_add_u64 v[216:217], s[6:7], 0, v[202:203]
	global_store_dwordx4 v[216:217], v[168:171], off offset:64
	v_lshl_add_u64 v[144:145], s[8:9], 0, v[202:203]
	global_load_dwordx4 v[168:171], v[144:145], off offset:512
	s_waitcnt vmcnt(14)
	v_pk_add_f32 v[172:173], v[172:173], v[76:77]
	v_pk_add_f32 v[174:175], v[174:175], v[78:79]
	v_lshl_add_u64 v[216:217], s[6:7], 0, v[204:205]
	global_store_dwordx4 v[216:217], v[172:175], off offset:64
	v_lshl_add_u64 v[144:145], s[8:9], 0, v[204:205]
	global_load_dwordx4 v[172:175], v[144:145], off offset:512
	s_waitcnt vmcnt(14)
	v_pk_add_f32 v[176:177], v[176:177], v[72:73]
	v_pk_add_f32 v[178:179], v[178:179], v[74:75]
	v_lshl_add_u64 v[216:217], s[6:7], 0, v[206:207]
	global_store_dwordx4 v[216:217], v[176:179], off offset:64
	v_lshl_add_u64 v[144:145], s[8:9], 0, v[206:207]
	global_load_dwordx4 v[176:179], v[144:145], off offset:512
	s_waitcnt vmcnt(14)
	v_pk_add_f32 v[212:213], v[212:213], v[68:69]
	v_pk_add_f32 v[214:215], v[214:215], v[70:71]
	v_lshl_add_u64 v[216:217], s[6:7], 0, v[208:209]
	global_store_dwordx4 v[216:217], v[212:215], off offset:64
	v_lshl_add_u64 v[144:145], s[8:9], 0, v[208:209]
	global_load_dwordx4 v[212:215], v[144:145], off offset:512
	s_waitcnt vmcnt(14)
; DI float sigmoidf_(float x) { return 1.0f / (1.0f + __expf(-x)); }
;     template <int W  > DI void flat_body(const f32x4 (&acc)[2][2][4][2], const int row0, const int col0) const {
;     ...
;                 for (int ai = 0; ai < 2; ++ai)
; #pragma unroll
;                     for (int m = 0; m < 4; ++m) {
;                         const size_t off = (size_t)(row0 + ai * HALF + m * 16) * ldc + col;
;                         f32x4 v = acc[ai][bj][m][n] + bv;
;                         if (W == 0) v = v + *(const f32x4*)((const float*)p1 + off);
;                         else if (W == 2) v = *(const f32x4*)((const float*)out + off) + 0.0f * v;
;                         else { v[0] = __expf(-0.60653066f * sigmoidf_(v[0])); v[1] = __expf(-0.60653066f * sigmoidf_(v[1])); v[2] = __expf(-0.60653066f * sigmoidf_(v[2])); v[3] = __expf(-0.60653066f * sigmoidf_(v[3])); }
;                         *(f32x4*)((float*)out + off) = v;
	v_pk_add_f32 v[140:141], v[140:141], v[64:65]
	v_pk_add_f32 v[142:143], v[142:143], v[66:67]
	v_lshl_add_u64 v[216:217], s[6:7], 0, v[210:211]
	global_store_dwordx4 v[216:217], v[140:143], off offset:64
	v_lshl_add_u64 v[144:145], s[8:9], 0, v[210:211]
	global_load_dwordx4 v[140:143], v[144:145], off offset:512
	s_waitcnt vmcnt(14)
	v_pk_add_f32 v[146:147], v[146:147], v[60:61]
	v_pk_add_f32 v[148:149], v[148:149], v[62:63]
	v_lshl_add_u64 v[216:217], s[6:7], 0, v[196:197]
	global_store_dwordx4 v[216:217], v[146:149], off offset:512
	v_lshl_add_u64 v[144:145], s[8:9], 0, v[196:197]
	global_load_dwordx4 v[146:149], v[144:145], off offset:576
	s_waitcnt vmcnt(14)
	v_pk_add_f32 v[150:151], v[150:151], v[56:57]
	v_pk_add_f32 v[152:153], v[152:153], v[58:59]
	v_lshl_add_u64 v[216:217], s[6:7], 0, v[198:199]
	global_store_dwordx4 v[216:217], v[150:153], off offset:512
	v_lshl_add_u64 v[144:145], s[8:9], 0, v[198:199]
	global_load_dwordx4 v[150:153], v[144:145], off offset:576
	s_waitcnt vmcnt(14)
	v_pk_add_f32 v[164:165], v[164:165], v[52:53]
	v_pk_add_f32 v[166:167], v[166:167], v[54:55]
	v_lshl_add_u64 v[216:217], s[6:7], 0, v[200:201]
	global_store_dwordx4 v[216:217], v[164:167], off offset:512
	v_lshl_add_u64 v[144:145], s[8:9], 0, v[200:201]
	global_load_dwordx4 v[164:167], v[144:145], off offset:576
	s_waitcnt vmcnt(14)
	v_pk_add_f32 v[168:169], v[168:169], v[48:49]
	v_pk_add_f32 v[170:171], v[170:171], v[50:51]
	v_lshl_add_u64 v[216:217], s[6:7], 0, v[202:203]
	global_store_dwordx4 v[216:217], v[168:171], off offset:512
	v_lshl_add_u64 v[144:145], s[8:9], 0, v[202:203]
	global_load_dwordx4 v[168:171], v[144:145], off offset:576
	s_waitcnt vmcnt(14)
	v_pk_add_f32 v[172:173], v[172:173], v[44:45]
	v_pk_add_f32 v[174:175], v[174:175], v[46:47]
	v_lshl_add_u64 v[216:217], s[6:7], 0, v[204:205]
	global_store_dwordx4 v[216:217], v[172:175], off offset:512
	v_lshl_add_u64 v[144:145], s[8:9], 0, v[204:205]
	global_load_dwordx4 v[172:175], v[144:145], off offset:576
	s_waitcnt vmcnt(14)
	v_pk_add_f32 v[176:177], v[176:177], v[40:41]
	v_pk_add_f32 v[178:179], v[178:179], v[42:43]
	v_lshl_add_u64 v[216:217], s[6:7], 0, v[206:207]
	global_store_dwordx4 v[216:217], v[176:179], off offset:512
	v_lshl_add_u64 v[144:145], s[8:9], 0, v[206:207]
	global_load_dwordx4 v[176:179], v[144:145], off offset:576
	s_waitcnt vmcnt(14)
	v_pk_add_f32 v[212:213], v[212:213], v[36:37]
	v_pk_add_f32 v[214:215], v[214:215], v[38:39]
	v_lshl_add_u64 v[216:217], s[6:7], 0, v[208:209]
	global_store_dwordx4 v[216:217], v[212:215], off offset:512
	v_lshl_add_u64 v[144:145], s[8:9], 0, v[208:209]
	global_load_dwordx4 v[212:215], v[144:145], off offset:576
	s_waitcnt vmcnt(14)
	v_pk_add_f32 v[140:141], v[140:141], v[32:33]
	v_pk_add_f32 v[142:143], v[142:143], v[34:35]
	v_lshl_add_u64 v[216:217], s[6:7], 0, v[210:211]
	global_store_dwordx4 v[216:217], v[140:143], off offset:512
	v_lshl_add_u64 v[144:145], s[8:9], 0, v[210:211]
	global_load_dwordx4 v[140:143], v[144:145], off offset:576
	s_waitcnt vmcnt(14)
	v_pk_add_f32 v[146:147], v[146:147], v[28:29]
	v_pk_add_f32 v[148:149], v[148:149], v[30:31]
	v_lshl_add_u64 v[216:217], s[6:7], 0, v[196:197]
	global_store_dwordx4 v[216:217], v[146:149], off offset:576
	s_waitcnt vmcnt(13)
	v_pk_add_f32 v[150:151], v[150:151], v[24:25]
	v_pk_add_f32 v[152:153], v[152:153], v[26:27]
	v_lshl_add_u64 v[216:217], s[6:7], 0, v[198:199]
	global_store_dwordx4 v[216:217], v[150:153], off offset:576
	s_waitcnt vmcnt(12)
	v_pk_add_f32 v[164:165], v[164:165], v[20:21]
	v_pk_add_f32 v[166:167], v[166:167], v[22:23]
	v_lshl_add_u64 v[216:217], s[6:7], 0, v[200:201]
	global_store_dwordx4 v[216:217], v[164:167], off offset:576
	s_waitcnt vmcnt(11)
	v_pk_add_f32 v[168:169], v[168:169], v[16:17]
	v_pk_add_f32 v[170:171], v[170:171], v[18:19]
	v_lshl_add_u64 v[216:217], s[6:7], 0, v[202:203]
	global_store_dwordx4 v[216:217], v[168:171], off offset:576
	s_waitcnt vmcnt(10)
	v_pk_add_f32 v[172:173], v[172:173], v[12:13]
	v_pk_add_f32 v[174:175], v[174:175], v[14:15]
	v_lshl_add_u64 v[216:217], s[6:7], 0, v[204:205]
	global_store_dwordx4 v[216:217], v[172:175], off offset:576
	s_waitcnt vmcnt(9)
	v_pk_add_f32 v[176:177], v[176:177], v[8:9]
	v_pk_add_f32 v[178:179], v[178:179], v[10:11]
	v_lshl_add_u64 v[216:217], s[6:7], 0, v[206:207]
	global_store_dwordx4 v[216:217], v[176:179], off offset:576
	s_waitcnt vmcnt(8)
	v_pk_add_f32 v[212:213], v[212:213], v[4:5]
	v_pk_add_f32 v[214:215], v[214:215], v[6:7]
	v_lshl_add_u64 v[216:217], s[6:7], 0, v[208:209]
	global_store_dwordx4 v[216:217], v[212:215], off offset:576
	s_waitcnt vmcnt(7)
	v_pk_add_f32 v[140:141], v[140:141], v[0:1]
	v_pk_add_f32 v[142:143], v[142:143], v[2:3]
	v_lshl_add_u64 v[216:217], s[6:7], 0, v[210:211]
	global_store_dwordx4 v[216:217], v[140:143], off offset:576
	s_and_b64 vcc, exec, s[38:39]
	s_mov_b64 s[0:1], -1
	s_cbranch_vccnz .LBB0_809
	s_branch .LBB0_859
